# lora-input phase: previous-row unpack deferred so its four loads share one wait
# baseline (speedup 1.0000x reference)
.LBB0_667:
	s_mov_b32 s0, 0x2aaaaaab
	v_mul_hi_i32 v1, v0, s0
	v_lshrrev_b32_e32 v4, 31, v1
	v_ashrrev_i32_e32 v1, 5, v1
	v_add_u32_e32 v6, v1, v4
	v_mad_u64_u32 v[10:11], s[0:1], v6, s19, v[0:1]
	v_mad_u64_u32 v[4:5], s[0:1], v6, s20, v[2:3]
	v_cmp_lt_i32_e32 vcc, s21, v0
	v_cmp_lt_i32_e64 s[0:1], s22, v10
	s_or_b64 s[0:1], vcc, s[0:1]
	v_ashrrev_i32_e32 v1, 31, v6
	v_ashrrev_i32_e32 v5, 31, v4
	s_and_saveexec_b64 s[14:15], s[0:1]
	s_xor_b64 s[0:1], exec, s[14:15]
	s_or_saveexec_b64 s[0:1], s[0:1]
	v_mov_b32_e32 v8, 0
	s_xor_b64 exec, exec, s[0:1]
	s_cbranch_execz .LBB0_666
	v_add_u32_e32 v8, 0xc00, v4
	v_mov_b64_e32 v[12:13], s[8:9]
	v_mad_i64_i32 v[12:13], s[14:15], v6, s23, v[12:13]
	v_ashrrev_i32_e32 v9, 31, v8
	v_lshl_add_u64 v[12:13], v[8:9], 1, v[12:13]
	global_load_dword v11, v[12:13], off
	v_cmp_gt_i32_e32 vcc, s24, v0
	s_nop 1
	v_cndmask_b32_e32 v12, 15, v7, vcc
	v_and_b32_e32 v12, v12, v6
	v_cmp_ne_u32_e32 vcc, 0, v12
	s_mov_b64 s[60:61], 0
	s_and_saveexec_b64 s[14:15], vcc
	s_xor_b64 s[14:15], exec, s[14:15]
	s_cbranch_execz .LBB0_672
	v_add_u32_e32 v16, -1, v6
	v_mov_b64_e32 v[12:13], s[8:9]
	v_mad_i64_i32 v[12:13], s[16:17], v16, s23, v[12:13]
	v_lshl_add_u64 v[12:13], v[8:9], 1, v[12:13]
	global_load_dword v13, v[12:13], off
	s_mov_b64 s[60:61], exec

.LBB0_676:
	s_or_b64 exec, exec, s[14:15]
	v_readlane_b32 s44, v239, 33
	v_readlane_b32 s45, v239, 34
	v_readlane_b32 s46, v239, 35
	v_readlane_b32 s47, v239, 36
	s_mov_b64 s[36:37], s[44:45]
	v_lshl_add_u64 v[16:17], v[4:5], 2, s[36:37]
	v_lshl_add_u64 v[8:9], v[8:9], 2, s[36:37]
	v_add_co_u32_e32 v16, vcc, 0x3000, v16
	v_readlane_b32 s48, v239, 37
	s_nop 0
	v_addc_co_u32_e32 v17, vcc, 0, v17, vcc
	global_load_dword v8, v[8:9], off
	s_nop 0
	global_load_dword v9, v[16:17], off offset:4
	s_waitcnt vmcnt(0)
	s_mov_b64 s[62:63], exec
	s_mov_b64 exec, s[60:61]
	v_lshlrev_b32_e32 v12, 16, v13
	v_and_b32_e32 v13, 0xffff0000, v13
	s_mov_b64 exec, s[62:63]
	v_lshlrev_b32_e32 v16, 16, v11
	v_and_b32_e32 v17, 0xffff0000, v11
	v_pk_add_f32 v[12:13], v[12:13], v[16:17] neg_lo:[0,1] neg_hi:[0,1]
	v_cmp_lt_i32_e32 vcc, 31, v10
	v_readlane_b32 s49, v239, 38
	v_readlane_b32 s50, v239, 39
	v_readlane_b32 s51, v239, 40
	v_readlane_b32 s52, v239, 41
	v_readlane_b32 s53, v239, 42
	v_readlane_b32 s54, v239, 43
	v_readlane_b32 s55, v239, 44
	v_readlane_b32 s56, v239, 45
	v_readlane_b32 s57, v239, 46
	v_readlane_b32 s58, v239, 47
	v_readlane_b32 s59, v239, 48
	s_mov_b64 s[38:39], s[46:47]
	v_pk_fma_f32 v[8:9], v[12:13], v[8:9], v[16:17]
	s_and_saveexec_b64 s[14:15], vcc
	s_xor_b64 s[14:15], exec, s[14:15]
	s_cbranch_execz .LBB0_680
	v_cmp_lt_u32_e32 vcc, 63, v10
	s_and_saveexec_b64 s[16:17], vcc
	s_cbranch_execz .LBB0_679
	v_mul_f32_e32 v8, 0xbfb8aa3b, v8
	v_mul_f32_e32 v9, 0xbfb8aa3b, v9
	v_exp_f32_e32 v8, v8
	v_exp_f32_e32 v9, v9
	s_nop 0
	v_pk_add_f32 v[8:9], v[8:9], 1.0 op_sel_hi:[1,0]
	s_nop 0
	v_div_scale_f32 v10, s[44:45], v8, v8, 1.0
	v_rcp_f32_e32 v11, v10
	s_nop 0
	v_fma_f32 v12, -v10, v11, 1.0
	v_fmac_f32_e32 v11, v12, v11
	v_div_scale_f32 v12, vcc, 1.0, v8, 1.0
	v_mul_f32_e32 v13, v12, v11
	v_fma_f32 v16, -v10, v13, v12
	v_fmac_f32_e32 v13, v16, v11
	v_fma_f32 v10, -v10, v13, v12
	v_div_fmas_f32 v10, v10, v11, v13
	v_div_fixup_f32 v8, v10, v8, 1.0
	v_div_scale_f32 v10, s[44:45], v9, v9, 1.0
	v_rcp_f32_e32 v11, v10
	s_nop 0
	v_fma_f32 v12, -v10, v11, 1.0
	v_fmac_f32_e32 v11, v12, v11
	v_div_scale_f32 v12, vcc, 1.0, v9, 1.0
	v_mul_f32_e32 v13, v12, v11
	v_fma_f32 v16, -v10, v13, v12
	v_fmac_f32_e32 v13, v16, v11
	v_fma_f32 v10, -v10, v13, v12
	v_div_fmas_f32 v10, v10, v11, v13
	v_div_fixup_f32 v9, v10, v9, 1.0
